# MoBA loop tile softmax/PV block regenerated: exp in place, P fragments in idle K buffers, only 8 exps + 4 cvts before the first PV MFMA, l-adds deferred into MFMA gaps
# speedup vs baseline: 1.0054x; 1.0054x over previous
.LBB0_78:
	v_exp_f32_e32 v80, v80
	v_exp_f32_e32 v81, v81
	v_exp_f32_e32 v82, v82
	v_exp_f32_e32 v83, v83
	v_exp_f32_e32 v84, v84
	v_exp_f32_e32 v85, v85
	v_exp_f32_e32 v86, v86
	v_exp_f32_e32 v87, v87
	v_cvt_pk_bf16_f32 v170, v80, v81
	v_cvt_pk_bf16_f32 v171, v82, v83
	v_cvt_pk_bf16_f32 v172, v84, v85
	v_cvt_pk_bf16_f32 v173, v86, v87
	v_add_f32_e32 v168, v168, v80
	s_waitcnt lgkmcnt(6)
	v_mfma_f32_32x32x16_bf16 v[48:63], v[188:191], v[170:173], v[48:63]
	v_exp_f32_e32 v88, v88
	v_exp_f32_e32 v89, v89
	v_add_f32_e32 v168, v168, v81
	v_cvt_pk_bf16_f32 v174, v88, v89
	ds_read_b64_tr_b16 v[188:189], v96 offset:20480
	ds_read_b64_tr_b16 v[190:191], v96 offset:22528
	s_waitcnt lgkmcnt(6)
	v_mfma_f32_32x32x16_bf16 v[32:47], v[192:195], v[170:173], v[32:47]
	v_exp_f32_e32 v90, v90
	v_exp_f32_e32 v91, v91
	v_add_f32_e32 v168, v168, v82
	v_cvt_pk_bf16_f32 v175, v90, v91
	ds_read_b64_tr_b16 v[192:193], v132 offset:20480
	ds_read_b64_tr_b16 v[194:195], v132 offset:22528
	s_waitcnt lgkmcnt(6)
	v_mfma_f32_32x32x16_bf16 v[16:31], v[198:201], v[170:173], v[16:31]
	v_exp_f32_e32 v92, v92
	v_exp_f32_e32 v93, v93
	v_add_f32_e32 v168, v168, v83
	v_cvt_pk_bf16_f32 v176, v92, v93
	ds_read_b64_tr_b16 v[198:199], v134 offset:20480
	ds_read_b64_tr_b16 v[200:201], v134 offset:22528
	s_waitcnt lgkmcnt(6)
	v_mfma_f32_32x32x16_bf16 v[0:15], v[202:205], v[170:173], v[0:15]
	v_exp_f32_e32 v94, v94
	v_exp_f32_e32 v95, v95
	v_add_f32_e32 v168, v168, v84
	v_cvt_pk_bf16_f32 v177, v94, v95
	ds_read_b64_tr_b16 v[202:203], v135 offset:20480
	ds_read_b64_tr_b16 v[204:205], v135 offset:22528
	s_waitcnt lgkmcnt(6)
	v_mfma_f32_32x32x16_bf16 v[48:63], v[188:191], v[174:177], v[48:63]
	v_exp_f32_e32 v64, v64
	v_exp_f32_e32 v65, v65
	v_add_f32_e32 v168, v168, v85
	v_cvt_pk_bf16_f32 v178, v64, v65
	ds_read_b64_tr_b16 v[188:189], v96 offset:24576
	ds_read_b64_tr_b16 v[190:191], v96 offset:26624
	s_waitcnt lgkmcnt(6)
	v_mfma_f32_32x32x16_bf16 v[32:47], v[192:195], v[174:177], v[32:47]
	v_exp_f32_e32 v66, v66
	v_exp_f32_e32 v67, v67
	v_add_f32_e32 v168, v168, v86
	v_cvt_pk_bf16_f32 v179, v66, v67
	ds_read_b64_tr_b16 v[192:193], v132 offset:24576
	ds_read_b64_tr_b16 v[194:195], v132 offset:26624
	s_waitcnt lgkmcnt(6)
	v_mfma_f32_32x32x16_bf16 v[16:31], v[198:201], v[174:177], v[16:31]
	v_exp_f32_e32 v68, v68
	v_exp_f32_e32 v69, v69
	v_add_f32_e32 v168, v168, v87
	v_cvt_pk_bf16_f32 v180, v68, v69
	ds_read_b64_tr_b16 v[198:199], v134 offset:24576
	ds_read_b64_tr_b16 v[200:201], v134 offset:26624
	s_waitcnt lgkmcnt(6)
	v_mfma_f32_32x32x16_bf16 v[0:15], v[202:205], v[174:177], v[0:15]
	v_exp_f32_e32 v70, v70
	v_exp_f32_e32 v71, v71
	v_add_f32_e32 v168, v168, v88
	v_cvt_pk_bf16_f32 v181, v70, v71
	ds_read_b64_tr_b16 v[202:203], v135 offset:24576
	ds_read_b64_tr_b16 v[204:205], v135 offset:26624
	s_waitcnt lgkmcnt(6)
	v_mfma_f32_32x32x16_bf16 v[48:63], v[188:191], v[178:181], v[48:63]
	v_exp_f32_e32 v72, v72
	v_exp_f32_e32 v73, v73
	v_add_f32_e32 v168, v168, v89
	v_cvt_pk_bf16_f32 v80, v72, v73
	ds_read_b64_tr_b16 v[188:189], v96 offset:28672
	ds_read_b64_tr_b16 v[190:191], v96 offset:30720
	s_waitcnt lgkmcnt(6)
	v_mfma_f32_32x32x16_bf16 v[32:47], v[192:195], v[178:181], v[32:47]
	v_exp_f32_e32 v74, v74
	v_exp_f32_e32 v75, v75
	v_add_f32_e32 v168, v168, v90
	v_cvt_pk_bf16_f32 v81, v74, v75
	ds_read_b64_tr_b16 v[192:193], v132 offset:28672
	ds_read_b64_tr_b16 v[194:195], v132 offset:30720
	s_waitcnt lgkmcnt(6)
	v_mfma_f32_32x32x16_bf16 v[16:31], v[198:201], v[178:181], v[16:31]
	v_exp_f32_e32 v76, v76
	v_exp_f32_e32 v77, v77
	v_add_f32_e32 v168, v168, v91
	v_cvt_pk_bf16_f32 v82, v76, v77
	ds_read_b64_tr_b16 v[198:199], v134 offset:28672
	ds_read_b64_tr_b16 v[200:201], v134 offset:30720
	s_waitcnt lgkmcnt(6)
	v_mfma_f32_32x32x16_bf16 v[0:15], v[202:205], v[178:181], v[0:15]
	v_exp_f32_e32 v78, v78
	v_exp_f32_e32 v79, v79
	v_add_f32_e32 v168, v168, v92
	v_cvt_pk_bf16_f32 v83, v78, v79
	ds_read_b64_tr_b16 v[202:203], v135 offset:28672
	ds_read_b64_tr_b16 v[204:205], v135 offset:30720
	s_waitcnt lgkmcnt(6)
	v_mfma_f32_32x32x16_bf16 v[48:63], v[188:191], v[80:83], v[48:63]
	v_add_f32_e32 v168, v168, v93
	v_add_f32_e32 v168, v168, v94
	v_add_f32_e32 v168, v168, v95
	v_add_f32_e32 v168, v168, v64
	v_add_f32_e32 v168, v168, v65
	v_add_f32_e32 v168, v168, v66
	v_add_f32_e32 v168, v168, v67
	s_waitcnt lgkmcnt(4)
	v_mfma_f32_32x32x16_bf16 v[32:47], v[192:195], v[80:83], v[32:47]
	v_add_f32_e32 v168, v168, v68
	v_add_f32_e32 v168, v168, v69
	v_add_f32_e32 v168, v168, v70
	v_add_f32_e32 v168, v168, v71
	v_add_f32_e32 v168, v168, v72
	v_add_f32_e32 v168, v168, v73
	s_waitcnt lgkmcnt(2)
	v_mfma_f32_32x32x16_bf16 v[16:31], v[198:201], v[80:83], v[16:31]
	v_add_f32_e32 v168, v168, v74
	v_add_f32_e32 v168, v168, v75
	v_add_f32_e32 v168, v168, v76
	v_add_f32_e32 v168, v168, v77
	v_add_f32_e32 v168, v168, v78
	v_add_f32_e32 v168, v168, v79
	s_waitcnt lgkmcnt(0)
	v_mfma_f32_32x32x16_bf16 v[0:15], v[202:205], v[80:83], v[0:15]

.LBB0_88:
	v_exp_f32_e32 v80, v80
	v_exp_f32_e32 v81, v81
	v_exp_f32_e32 v82, v82
	v_exp_f32_e32 v83, v83
	v_exp_f32_e32 v84, v84
	v_exp_f32_e32 v85, v85
	v_exp_f32_e32 v86, v86
	v_exp_f32_e32 v87, v87
	v_cvt_pk_bf16_f32 v170, v80, v81
	v_cvt_pk_bf16_f32 v171, v82, v83
	v_cvt_pk_bf16_f32 v172, v84, v85
	v_cvt_pk_bf16_f32 v173, v86, v87
	v_add_f32_e32 v168, v168, v80
	s_waitcnt lgkmcnt(6)
	v_mfma_f32_32x32x16_bf16 v[48:63], v[188:191], v[170:173], v[48:63]
	v_exp_f32_e32 v88, v88
	v_exp_f32_e32 v89, v89
	v_add_f32_e32 v168, v168, v81
	v_cvt_pk_bf16_f32 v174, v88, v89
	ds_read_b64_tr_b16 v[188:189], v96 offset:53248
	ds_read_b64_tr_b16 v[190:191], v96 offset:55296
	s_waitcnt lgkmcnt(6)
	v_mfma_f32_32x32x16_bf16 v[32:47], v[192:195], v[170:173], v[32:47]
	v_exp_f32_e32 v90, v90
	v_exp_f32_e32 v91, v91
	v_add_f32_e32 v168, v168, v82
	v_cvt_pk_bf16_f32 v175, v90, v91
	ds_read_b64_tr_b16 v[192:193], v132 offset:53248
	ds_read_b64_tr_b16 v[194:195], v132 offset:55296
	s_waitcnt lgkmcnt(6)
	v_mfma_f32_32x32x16_bf16 v[16:31], v[198:201], v[170:173], v[16:31]
	v_exp_f32_e32 v92, v92
	v_exp_f32_e32 v93, v93
	v_add_f32_e32 v168, v168, v83
	v_cvt_pk_bf16_f32 v176, v92, v93
	ds_read_b64_tr_b16 v[198:199], v134 offset:53248
	ds_read_b64_tr_b16 v[200:201], v134 offset:55296
	s_waitcnt lgkmcnt(6)
	v_mfma_f32_32x32x16_bf16 v[0:15], v[202:205], v[170:173], v[0:15]
	v_exp_f32_e32 v94, v94
	v_exp_f32_e32 v95, v95
	v_add_f32_e32 v168, v168, v84
	v_cvt_pk_bf16_f32 v177, v94, v95
	ds_read_b64_tr_b16 v[202:203], v135 offset:53248
	ds_read_b64_tr_b16 v[204:205], v135 offset:55296
	s_waitcnt lgkmcnt(6)
	v_mfma_f32_32x32x16_bf16 v[48:63], v[188:191], v[174:177], v[48:63]
	v_exp_f32_e32 v64, v64
	v_exp_f32_e32 v65, v65
	v_add_f32_e32 v168, v168, v85
	v_cvt_pk_bf16_f32 v178, v64, v65
	ds_read_b64_tr_b16 v[188:189], v96 offset:57344
	ds_read_b64_tr_b16 v[190:191], v96 offset:59392
	s_waitcnt lgkmcnt(6)
	v_mfma_f32_32x32x16_bf16 v[32:47], v[192:195], v[174:177], v[32:47]
	v_exp_f32_e32 v66, v66
	v_exp_f32_e32 v67, v67
	v_add_f32_e32 v168, v168, v86
	v_cvt_pk_bf16_f32 v179, v66, v67
	ds_read_b64_tr_b16 v[192:193], v132 offset:57344
	ds_read_b64_tr_b16 v[194:195], v132 offset:59392
	s_waitcnt lgkmcnt(6)
	v_mfma_f32_32x32x16_bf16 v[16:31], v[198:201], v[174:177], v[16:31]
	v_exp_f32_e32 v68, v68
	v_exp_f32_e32 v69, v69
	v_add_f32_e32 v168, v168, v87
	v_cvt_pk_bf16_f32 v180, v68, v69
	ds_read_b64_tr_b16 v[198:199], v134 offset:57344
	ds_read_b64_tr_b16 v[200:201], v134 offset:59392
	s_waitcnt lgkmcnt(6)
	v_mfma_f32_32x32x16_bf16 v[0:15], v[202:205], v[174:177], v[0:15]
	v_exp_f32_e32 v70, v70
	v_exp_f32_e32 v71, v71
	v_add_f32_e32 v168, v168, v88
	v_cvt_pk_bf16_f32 v181, v70, v71
	ds_read_b64_tr_b16 v[202:203], v135 offset:57344
	ds_read_b64_tr_b16 v[204:205], v135 offset:59392
	s_waitcnt lgkmcnt(6)
	v_mfma_f32_32x32x16_bf16 v[48:63], v[188:191], v[178:181], v[48:63]
	v_exp_f32_e32 v72, v72
	v_exp_f32_e32 v73, v73
	v_add_f32_e32 v168, v168, v89
	v_cvt_pk_bf16_f32 v80, v72, v73
	ds_read_b64_tr_b16 v[188:189], v96 offset:61440
	ds_read_b64_tr_b16 v[190:191], v96 offset:63488
	s_waitcnt lgkmcnt(6)
	v_mfma_f32_32x32x16_bf16 v[32:47], v[192:195], v[178:181], v[32:47]
	v_exp_f32_e32 v74, v74
	v_exp_f32_e32 v75, v75
	v_add_f32_e32 v168, v168, v90
	v_cvt_pk_bf16_f32 v81, v74, v75
	ds_read_b64_tr_b16 v[192:193], v132 offset:61440
	ds_read_b64_tr_b16 v[194:195], v132 offset:63488
	s_waitcnt lgkmcnt(6)
	v_mfma_f32_32x32x16_bf16 v[16:31], v[198:201], v[178:181], v[16:31]
	v_exp_f32_e32 v76, v76
	v_exp_f32_e32 v77, v77
	v_add_f32_e32 v168, v168, v91
	v_cvt_pk_bf16_f32 v82, v76, v77
	ds_read_b64_tr_b16 v[198:199], v134 offset:61440
	ds_read_b64_tr_b16 v[200:201], v134 offset:63488
	s_waitcnt lgkmcnt(6)
	v_mfma_f32_32x32x16_bf16 v[0:15], v[202:205], v[178:181], v[0:15]
	v_exp_f32_e32 v78, v78
	v_exp_f32_e32 v79, v79
	v_add_f32_e32 v168, v168, v92
	v_cvt_pk_bf16_f32 v83, v78, v79
	ds_read_b64_tr_b16 v[202:203], v135 offset:61440
	ds_read_b64_tr_b16 v[204:205], v135 offset:63488
	s_waitcnt lgkmcnt(6)
	v_mfma_f32_32x32x16_bf16 v[48:63], v[188:191], v[80:83], v[48:63]
	v_add_f32_e32 v168, v168, v93
	v_add_f32_e32 v168, v168, v94
	v_add_f32_e32 v168, v168, v95
	v_add_f32_e32 v168, v168, v64
	v_add_f32_e32 v168, v168, v65
	v_add_f32_e32 v168, v168, v66
	v_add_f32_e32 v168, v168, v67
	s_waitcnt lgkmcnt(4)
	v_mfma_f32_32x32x16_bf16 v[32:47], v[192:195], v[80:83], v[32:47]
	v_add_f32_e32 v168, v168, v68
	v_add_f32_e32 v168, v168, v69
	v_add_f32_e32 v168, v168, v70
	v_add_f32_e32 v168, v168, v71
	v_add_f32_e32 v168, v168, v72
	v_add_f32_e32 v168, v168, v73
	s_waitcnt lgkmcnt(2)
	v_mfma_f32_32x32x16_bf16 v[16:31], v[198:201], v[80:83], v[16:31]
	v_add_f32_e32 v168, v168, v74
	v_add_f32_e32 v168, v168, v75
	v_add_f32_e32 v168, v168, v76
	v_add_f32_e32 v168, v168, v77
	v_add_f32_e32 v168, v168, v78
	v_add_f32_e32 v168, v168, v79
	s_waitcnt lgkmcnt(0)
	v_mfma_f32_32x32x16_bf16 v[0:15], v[202:205], v[80:83], v[0:15]
